# accumulator zeroing per GEMM tile: 64 v_mov_b64 instead of 128 v_mov_b32 (3 GEMM bodies)
# baseline (speedup 1.0000x reference)
.LBB0_74:
	s_ashr_i32 s63, s62, 31
	s_lshl_b64 s[68:69], s[62:63], 19
	s_add_u32 s76, s36, s68
	s_addc_u32 s77, s37, s69
	s_and_b64 s[68:69], s[38:39], exec
	s_cselect_b32 s2, s77, s91
	s_cselect_b32 s6, s76, s90
	s_ashr_i32 s51, s50, 31
	s_lshl_b64 s[68:69], s[50:51], 19
	s_add_u32 s78, s42, s68
	s_addc_u32 s79, s43, s69
	s_and_b64 s[68:69], s[38:39], exec
	s_cselect_b32 s51, s79, s93
	s_cselect_b32 s63, s78, s92
	s_add_u32 s90, s90, 0x40080
	s_addc_u32 s91, s91, 0
	s_add_u32 s89, s92, 0x100
	v_mov_b64_e32 v[2:3], 0
	v_mov_b64_e32 v[4:5], 0
	v_mov_b64_e32 v[6:7], 0
	v_mov_b64_e32 v[8:9], 0
	v_mov_b64_e32 v[10:11], 0
	v_mov_b64_e32 v[12:13], 0
	v_mov_b64_e32 v[14:15], 0
	v_mov_b64_e32 v[16:17], 0
	v_mov_b64_e32 v[18:19], 0
	v_mov_b64_e32 v[20:21], 0
	v_mov_b64_e32 v[22:23], 0
	v_mov_b64_e32 v[24:25], 0
	v_mov_b64_e32 v[26:27], 0
	v_mov_b64_e32 v[28:29], 0
	v_mov_b64_e32 v[30:31], 0
	v_mov_b64_e32 v[32:33], 0
	v_mov_b64_e32 v[34:35], 0
	v_mov_b64_e32 v[36:37], 0
	v_mov_b64_e32 v[38:39], 0
	v_mov_b64_e32 v[40:41], 0
	v_mov_b64_e32 v[42:43], 0
	v_mov_b64_e32 v[44:45], 0
	v_mov_b64_e32 v[46:47], 0
	v_mov_b64_e32 v[48:49], 0
	v_mov_b64_e32 v[50:51], 0
	v_mov_b64_e32 v[52:53], 0
	v_mov_b64_e32 v[54:55], 0
	v_mov_b64_e32 v[56:57], 0
	v_mov_b64_e32 v[58:59], 0
	v_mov_b64_e32 v[60:61], 0
	v_mov_b64_e32 v[62:63], 0
	v_mov_b64_e32 v[64:65], 0
	v_mov_b64_e32 v[66:67], 0
	v_mov_b64_e32 v[68:69], 0
	v_mov_b64_e32 v[70:71], 0
	v_mov_b64_e32 v[72:73], 0
	v_mov_b64_e32 v[74:75], 0
	v_mov_b64_e32 v[76:77], 0
	v_mov_b64_e32 v[78:79], 0
	v_mov_b64_e32 v[80:81], 0
	v_mov_b64_e32 v[82:83], 0
	v_mov_b64_e32 v[84:85], 0
	v_mov_b64_e32 v[86:87], 0
	v_mov_b64_e32 v[88:89], 0
	v_mov_b64_e32 v[90:91], 0
	v_mov_b64_e32 v[92:93], 0
	v_mov_b64_e32 v[94:95], 0
	v_mov_b64_e32 v[96:97], 0
	v_mov_b64_e32 v[98:99], 0
	v_mov_b64_e32 v[100:101], 0
	v_mov_b64_e32 v[102:103], 0
	v_mov_b64_e32 v[104:105], 0
	v_mov_b64_e32 v[106:107], 0
	v_mov_b64_e32 v[108:109], 0
	v_mov_b64_e32 v[110:111], 0
	v_mov_b64_e32 v[112:113], 0
	v_mov_b64_e32 v[114:115], 0
	v_mov_b64_e32 v[116:117], 0
	v_mov_b64_e32 v[118:119], 0
	v_mov_b64_e32 v[120:121], 0
	v_mov_b64_e32 v[122:123], 0
	v_mov_b64_e32 v[124:125], 0
	v_mov_b64_e32 v[126:127], 0
	v_mov_b64_e32 v[128:129], 0
	s_addc_u32 s96, s93, 0
	s_mov_b32 s97, -2

.LBB0_187:
	s_add_u32 s40, s94, 0x80
	s_addc_u32 s41, s95, 0
	s_add_u32 s94, s92, 0x100
	v_mov_b64_e32 v[2:3], 0
	v_mov_b64_e32 v[4:5], 0
	v_mov_b64_e32 v[6:7], 0
	v_mov_b64_e32 v[8:9], 0
	v_mov_b64_e32 v[10:11], 0
	v_mov_b64_e32 v[12:13], 0
	v_mov_b64_e32 v[14:15], 0
	v_mov_b64_e32 v[16:17], 0
	v_mov_b64_e32 v[18:19], 0
	v_mov_b64_e32 v[20:21], 0
	v_mov_b64_e32 v[22:23], 0
	v_mov_b64_e32 v[24:25], 0
	v_mov_b64_e32 v[26:27], 0
	v_mov_b64_e32 v[28:29], 0
	v_mov_b64_e32 v[30:31], 0
	v_mov_b64_e32 v[32:33], 0
	v_mov_b64_e32 v[34:35], 0
	v_mov_b64_e32 v[36:37], 0
	v_mov_b64_e32 v[38:39], 0
	v_mov_b64_e32 v[40:41], 0
	v_mov_b64_e32 v[42:43], 0
	v_mov_b64_e32 v[44:45], 0
	v_mov_b64_e32 v[46:47], 0
	v_mov_b64_e32 v[48:49], 0
	v_mov_b64_e32 v[50:51], 0
	v_mov_b64_e32 v[52:53], 0
	v_mov_b64_e32 v[54:55], 0
	v_mov_b64_e32 v[56:57], 0
	v_mov_b64_e32 v[58:59], 0
	v_mov_b64_e32 v[60:61], 0
	v_mov_b64_e32 v[62:63], 0
	v_mov_b64_e32 v[64:65], 0
	v_mov_b64_e32 v[66:67], 0
	v_mov_b64_e32 v[68:69], 0
	v_mov_b64_e32 v[70:71], 0
	v_mov_b64_e32 v[72:73], 0
	v_mov_b64_e32 v[74:75], 0
	v_mov_b64_e32 v[76:77], 0
	v_mov_b64_e32 v[78:79], 0
	v_mov_b64_e32 v[80:81], 0
	v_mov_b64_e32 v[82:83], 0
	v_mov_b64_e32 v[84:85], 0
	v_mov_b64_e32 v[86:87], 0
	v_mov_b64_e32 v[88:89], 0
	v_mov_b64_e32 v[90:91], 0
	v_mov_b64_e32 v[92:93], 0
	v_mov_b64_e32 v[94:95], 0
	v_mov_b64_e32 v[96:97], 0
	v_mov_b64_e32 v[98:99], 0
	v_mov_b64_e32 v[100:101], 0
	v_mov_b64_e32 v[102:103], 0
	v_mov_b64_e32 v[104:105], 0
	v_mov_b64_e32 v[114:115], 0
	v_mov_b64_e32 v[116:117], 0
	v_mov_b64_e32 v[118:119], 0
	v_mov_b64_e32 v[120:121], 0
	v_mov_b64_e32 v[130:131], 0
	v_mov_b64_e32 v[132:133], 0
	v_mov_b64_e32 v[134:135], 0
	v_mov_b64_e32 v[136:137], 0
	v_mov_b64_e32 v[138:139], 0
	v_mov_b64_e32 v[140:141], 0
	v_mov_b64_e32 v[142:143], 0
	v_mov_b64_e32 v[144:145], 0
	s_addc_u32 s95, s93, 0
	s_mov_b32 s92, 0

.LBB0_242:
	s_ashr_i32 s95, s94, 31
	s_lshl_b64 s[70:71], s[94:95], 19
	s_add_u32 s90, s36, s70
	s_addc_u32 s91, s37, s71
	s_and_b64 s[70:71], s[38:39], exec
	s_cselect_b32 s2, s91, s43
	s_cselect_b32 s6, s90, s42
	s_ashr_i32 s89, s88, 31
	s_lshl_b64 s[70:71], s[88:89], 19
	s_add_u32 s96, s50, s70
	s_addc_u32 s97, s51, s71
	s_and_b64 s[70:71], s[38:39], exec
	s_cselect_b32 s41, s97, s93
	s_cselect_b32 s48, s96, s92
	s_add_u32 s42, s42, 0x40080
	s_addc_u32 s43, s43, 0
	s_add_u32 s77, s92, 0x100
	v_mov_b64_e32 v[2:3], 0
	v_mov_b64_e32 v[4:5], 0
	v_mov_b64_e32 v[6:7], 0
	v_mov_b64_e32 v[8:9], 0
	v_mov_b64_e32 v[10:11], 0
	v_mov_b64_e32 v[12:13], 0
	v_mov_b64_e32 v[18:19], 0
	v_mov_b64_e32 v[20:21], 0
	v_mov_b64_e32 v[30:31], 0
	v_mov_b64_e32 v[32:33], 0
	v_mov_b64_e32 v[34:35], 0
	v_mov_b64_e32 v[36:37], 0
	v_mov_b64_e32 v[38:39], 0
	v_mov_b64_e32 v[40:41], 0
	v_mov_b64_e32 v[42:43], 0
	v_mov_b64_e32 v[44:45], 0
	v_mov_b64_e32 v[46:47], 0
	v_mov_b64_e32 v[48:49], 0
	v_mov_b64_e32 v[50:51], 0
	v_mov_b64_e32 v[52:53], 0
	v_mov_b64_e32 v[54:55], 0
	v_mov_b64_e32 v[56:57], 0
	v_mov_b64_e32 v[58:59], 0
	v_mov_b64_e32 v[60:61], 0
	v_mov_b64_e32 v[62:63], 0
	v_mov_b64_e32 v[64:65], 0
	v_mov_b64_e32 v[66:67], 0
	v_mov_b64_e32 v[68:69], 0
	v_mov_b64_e32 v[70:71], 0
	v_mov_b64_e32 v[72:73], 0
	v_mov_b64_e32 v[86:87], 0
	v_mov_b64_e32 v[88:89], 0
	v_mov_b64_e32 v[90:91], 0
	v_mov_b64_e32 v[92:93], 0
	v_mov_b64_e32 v[94:95], 0
	v_mov_b64_e32 v[96:97], 0
	v_mov_b64_e32 v[98:99], 0
	v_mov_b64_e32 v[100:101], 0
	v_mov_b64_e32 v[102:103], 0
	v_mov_b64_e32 v[104:105], 0
	v_mov_b64_e32 v[106:107], 0
	v_mov_b64_e32 v[108:109], 0
	v_mov_b64_e32 v[110:111], 0
	v_mov_b64_e32 v[112:113], 0
	v_mov_b64_e32 v[114:115], 0
	v_mov_b64_e32 v[116:117], 0
	v_mov_b64_e32 v[118:119], 0
	v_mov_b64_e32 v[120:121], 0
	v_mov_b64_e32 v[122:123], 0
	v_mov_b64_e32 v[124:125], 0
	v_mov_b64_e32 v[126:127], 0
	v_mov_b64_e32 v[128:129], 0
	v_mov_b64_e32 v[130:131], 0
	v_mov_b64_e32 v[132:133], 0
	v_mov_b64_e32 v[134:135], 0
	v_mov_b64_e32 v[136:137], 0
	v_mov_b64_e32 v[138:139], 0
	v_mov_b64_e32 v[140:141], 0
	v_mov_b64_e32 v[142:143], 0
	v_mov_b64_e32 v[144:145], 0
	v_mov_b64_e32 v[146:147], 0
	v_mov_b64_e32 v[148:149], 0
	v_mov_b64_e32 v[150:151], 0
	v_mov_b64_e32 v[152:153], 0
	s_addc_u32 s89, s93, 0
	s_mov_b32 s95, -2
	s_waitcnt lgkmcnt(0)
